# strategy 7 instruction selection: adjacent scalar f32 mul/add pairs in the SwiGLU epilogue packed into v_pk_mul_f32/v_pk_add_f32 (bit-identical)
# speedup vs baseline: 1.0083x; 1.0056x over previous
.LBB0_700:
	s_mov_b32 s86, 1.0
	s_lshl_b32 s5, s16, 7
	s_or_b32 s5, s5, s75
	v_add_u32_e32 v128, s5, v176
	s_lshl_b32 s5, s17, 10
	s_add_i32 s5, s5, 0
	s_add_i32 s5, s5, 0x21400
	v_lshl_add_u32 v130, v175, 2, s5
	ds_read_b32 v130, v130
	v_pk_mul_f32 v[120:121], v[124:125], v[120:121]
	v_pk_mul_f32 v[122:123], v[126:127], v[122:123]
	v_pk_mul_f32 v[112:113], v[116:117], v[112:113]
	v_pk_mul_f32 v[114:115], v[118:119], v[114:115]
	s_waitcnt lgkmcnt(0)
	v_mul_f32_e32 v131, 0xbfb8aa3b, v130
	v_pk_mul_f32 v[144:145], v[124:125], v[130:131] op_sel:[0,1] op_sel_hi:[1,1]
	v_pk_mul_f32 v[124:125], v[126:127], v[130:131] op_sel:[0,1] op_sel_hi:[1,1]
	v_exp_f32_e32 v124, v124
	v_exp_f32_e32 v125, v125
	v_exp_f32_e32 v144, v144
	v_exp_f32_e32 v145, v145
	v_pk_add_f32 v[124:125], v[124:125], s[86:87] op_sel_hi:[1,0]
	v_rcp_f32_e32 v124, v124
	v_rcp_f32_e32 v125, v125
	v_pk_add_f32 v[144:145], v[144:145], s[86:87] op_sel_hi:[1,0]
	v_rcp_f32_e32 v144, v144
	v_pk_mul_f32 v[122:123], v[122:123], v[124:125]
	v_pk_mul_f32 v[124:125], v[116:117], v[130:131] op_sel:[0,1] op_sel_hi:[1,1]
	v_exp_f32_e32 v124, v124
	v_exp_f32_e32 v125, v125
	v_pk_mul_f32 v[116:117], v[118:119], v[130:131] op_sel:[0,1] op_sel_hi:[1,1]
	v_exp_f32_e32 v116, v116
	v_exp_f32_e32 v117, v117
	v_pk_add_f32 v[124:125], v[124:125], s[86:87] op_sel_hi:[1,0]
	v_rcp_f32_e32 v124, v124
	v_rcp_f32_e32 v125, v125
	v_pk_add_f32 v[116:117], v[116:117], s[86:87] op_sel_hi:[1,0]
	v_rcp_f32_e32 v145, v145
	v_rcp_f32_e32 v116, v116
	v_rcp_f32_e32 v117, v117
	v_mul_f32_e32 v130, v130, v130
	v_pk_mul_f32 v[112:113], v[112:113], v[124:125]
	v_pk_mul_f32 v[120:121], v[120:121], v[144:145]
	v_pk_mul_f32 v[112:113], v[130:131], v[112:113] op_sel_hi:[0,1]
	v_pk_mul_f32 v[114:115], v[114:115], v[116:117]
	v_ashrrev_i32_e32 v129, 31, v128
	v_pk_mul_f32 v[120:121], v[130:131], v[120:121] op_sel_hi:[0,1]
	v_pk_mul_f32 v[114:115], v[130:131], v[114:115] op_sel_hi:[0,1]
	v_cvt_pk_bf16_f32 v118, v112, v113
	v_mov_b64_e32 v[112:113], s[36:37]
	v_pk_mul_f32 v[122:123], v[130:131], v[122:123] op_sel_hi:[0,1]
	v_cvt_pk_bf16_f32 v116, v120, v121
	v_cvt_pk_bf16_f32 v119, v114, v115
	v_mad_i64_i32 v[120:121], s[16:17], v174, s72, v[112:113]
	v_lshlrev_b64 v[114:115], 1, v[128:129]
	v_cvt_pk_bf16_f32 v117, v122, v123
	v_lshl_add_u64 v[120:121], v[120:121], 0, v[114:115]
	global_store_dwordx4 v[120:121], v[116:119], off
	v_pk_mul_f32 v[104:105], v[108:109], v[104:105]
	v_pk_mul_f32 v[106:107], v[110:111], v[106:107]
	v_add_u32_e32 v117, 16, v174
	v_and_b32_e32 v116, 0xff, v117
	v_lshl_add_u32 v116, v116, 2, s5
	ds_read_b32 v116, v116
	v_pk_mul_f32 v[96:97], v[100:101], v[96:97]
	v_pk_mul_f32 v[98:99], v[102:103], v[98:99]
	v_pk_mul_f32 v[88:89], v[92:93], v[88:89]
	v_pk_mul_f32 v[90:91], v[94:95], v[90:91]
	s_waitcnt lgkmcnt(0)
	v_mul_f32_e32 v120, 0xbfb8aa3b, v116
	v_pk_mul_f32 v[118:119], v[108:109], v[120:121] op_sel_hi:[1,0]
	v_pk_mul_f32 v[108:109], v[110:111], v[120:121] op_sel_hi:[1,0]
	v_exp_f32_e32 v108, v108
	v_exp_f32_e32 v109, v109
	v_mul_f32_e32 v116, v116, v116
	v_exp_f32_e32 v118, v118
	v_pk_add_f32 v[108:109], v[108:109], s[86:87] op_sel_hi:[1,0]
	v_rcp_f32_e32 v108, v108
	v_rcp_f32_e32 v109, v109
	v_exp_f32_e32 v119, v119
	v_add_f32_e32 v118, 1.0, v118
	v_rcp_f32_e32 v118, v118
	v_pk_mul_f32 v[106:107], v[106:107], v[108:109]
	v_pk_mul_f32 v[108:109], v[100:101], v[120:121] op_sel_hi:[1,0]
	v_exp_f32_e32 v108, v108
	v_exp_f32_e32 v109, v109
	v_add_f32_e32 v119, 1.0, v119
	v_rcp_f32_e32 v119, v119
	v_pk_add_f32 v[108:109], v[108:109], s[86:87] op_sel_hi:[1,0]
	v_rcp_f32_e32 v108, v108
	v_rcp_f32_e32 v109, v109
	v_pk_mul_f32 v[104:105], v[104:105], v[118:119]
	v_pk_mul_f32 v[106:107], v[116:117], v[106:107] op_sel_hi:[0,1]
	v_pk_mul_f32 v[104:105], v[116:117], v[104:105] op_sel_hi:[0,1]
	v_pk_mul_f32 v[96:97], v[96:97], v[108:109]
	v_pk_mul_f32 v[80:81], v[84:85], v[80:81]
	v_pk_mul_f32 v[100:101], v[116:117], v[96:97] op_sel_hi:[0,1]
	v_pk_mul_f32 v[96:97], v[102:103], v[120:121] op_sel_hi:[1,0]
	v_exp_f32_e32 v96, v96
	v_exp_f32_e32 v97, v97
	v_pk_mul_f32 v[82:83], v[86:87], v[82:83]
	v_pk_mul_f32 v[72:73], v[76:77], v[72:73]
	v_pk_add_f32 v[96:97], v[96:97], s[86:87] op_sel_hi:[1,0]
	v_rcp_f32_e32 v96, v96
	v_rcp_f32_e32 v97, v97
	v_pk_mul_f32 v[74:75], v[78:79], v[74:75]
	v_pk_mul_f32 v[64:65], v[68:69], v[64:65]
	v_pk_mul_f32 v[66:67], v[70:71], v[66:67]
	v_pk_mul_f32 v[96:97], v[98:99], v[96:97]
	v_cvt_pk_bf16_f32 v98, v100, v101
	v_pk_mul_f32 v[102:103], v[116:117], v[96:97] op_sel_hi:[0,1]
	v_mad_i64_i32 v[100:101], s[16:17], v117, s72, v[112:113]
	v_cvt_pk_bf16_f32 v96, v104, v105
	v_cvt_pk_bf16_f32 v97, v106, v107
	v_cvt_pk_bf16_f32 v99, v102, v103
	v_lshl_add_u64 v[100:101], v[100:101], 0, v[114:115]
	global_store_dwordx4 v[100:101], v[96:99], off
	v_pk_mul_f32 v[56:57], v[60:61], v[56:57]
	v_pk_mul_f32 v[58:59], v[62:63], v[58:59]
	v_add_u32_e32 v97, 32, v174
	v_and_b32_e32 v96, 0xff, v97
	v_lshl_add_u32 v96, v96, 2, s5
	ds_read_b32 v96, v96
	v_pk_mul_f32 v[48:49], v[52:53], v[48:49]
	v_pk_mul_f32 v[50:51], v[54:55], v[50:51]
	v_pk_mul_f32 v[40:41], v[44:45], v[40:41]
	v_pk_mul_f32 v[42:43], v[46:47], v[42:43]
	s_waitcnt lgkmcnt(0)
	v_mul_f32_e32 v100, 0xbfb8aa3b, v96
	v_pk_mul_f32 v[98:99], v[92:93], v[100:101] op_sel_hi:[1,0]
	v_pk_mul_f32 v[92:93], v[94:95], v[100:101] op_sel_hi:[1,0]
	v_exp_f32_e32 v92, v92
	v_exp_f32_e32 v93, v93
	v_mul_f32_e32 v96, v96, v96
	v_exp_f32_e32 v98, v98
	v_pk_add_f32 v[92:93], v[92:93], s[86:87] op_sel_hi:[1,0]
	v_rcp_f32_e32 v92, v92
	v_rcp_f32_e32 v93, v93
	v_exp_f32_e32 v99, v99
	v_add_f32_e32 v98, 1.0, v98
	v_rcp_f32_e32 v98, v98
	v_pk_mul_f32 v[90:91], v[90:91], v[92:93]
	v_pk_mul_f32 v[92:93], v[84:85], v[100:101] op_sel_hi:[1,0]
	v_exp_f32_e32 v92, v92
	v_exp_f32_e32 v93, v93
	v_add_f32_e32 v99, 1.0, v99
	v_rcp_f32_e32 v99, v99
	v_pk_add_f32 v[92:93], v[92:93], s[86:87] op_sel_hi:[1,0]
	v_rcp_f32_e32 v92, v92
	v_rcp_f32_e32 v93, v93
	v_pk_mul_f32 v[88:89], v[88:89], v[98:99]
	v_pk_mul_f32 v[90:91], v[96:97], v[90:91] op_sel_hi:[0,1]
	v_pk_mul_f32 v[88:89], v[96:97], v[88:89] op_sel_hi:[0,1]
	v_pk_mul_f32 v[80:81], v[80:81], v[92:93]
	v_pk_mul_f32 v[32:33], v[36:37], v[32:33]
	v_pk_mul_f32 v[84:85], v[96:97], v[80:81] op_sel_hi:[0,1]
	v_pk_mul_f32 v[80:81], v[86:87], v[100:101] op_sel_hi:[1,0]
	v_exp_f32_e32 v80, v80
	v_exp_f32_e32 v81, v81
	v_pk_mul_f32 v[34:35], v[38:39], v[34:35]
	v_pk_mul_f32 v[24:25], v[28:29], v[24:25]
	v_pk_add_f32 v[80:81], v[80:81], s[86:87] op_sel_hi:[1,0]
	v_rcp_f32_e32 v80, v80
	v_rcp_f32_e32 v81, v81
	v_pk_mul_f32 v[26:27], v[30:31], v[26:27]
	v_pk_mul_f32 v[16:17], v[20:21], v[16:17]
	v_pk_mul_f32 v[18:19], v[22:23], v[18:19]
	v_pk_mul_f32 v[80:81], v[82:83], v[80:81]
	v_cvt_pk_bf16_f32 v82, v84, v85
	v_pk_mul_f32 v[86:87], v[96:97], v[80:81] op_sel_hi:[0,1]
	v_mad_i64_i32 v[84:85], s[16:17], v97, s72, v[112:113]
	v_cvt_pk_bf16_f32 v80, v88, v89
	v_cvt_pk_bf16_f32 v81, v90, v91
	v_cvt_pk_bf16_f32 v83, v86, v87
	v_lshl_add_u64 v[84:85], v[84:85], 0, v[114:115]
	global_store_dwordx4 v[84:85], v[80:83], off
	v_pk_mul_f32 v[0:1], v[4:5], v[0:1]
	v_pk_mul_f32 v[14:15], v[10:11], v[14:15]
	v_add_u32_e32 v81, 48, v174
	v_and_b32_e32 v80, 0xff, v81
	v_lshl_add_u32 v80, v80, 2, s5
	ds_read_b32 v80, v80
	v_pk_mul_f32 v[2:3], v[6:7], v[2:3]
	s_waitcnt lgkmcnt(0)
	v_mul_f32_e32 v84, 0xbfb8aa3b, v80
	v_pk_mul_f32 v[82:83], v[76:77], v[84:85] op_sel_hi:[1,0]
	v_pk_mul_f32 v[76:77], v[78:79], v[84:85] op_sel_hi:[1,0]
	v_exp_f32_e32 v76, v76
	v_exp_f32_e32 v77, v77
	v_mul_f32_e32 v80, v80, v80
	v_exp_f32_e32 v82, v82
	v_pk_add_f32 v[76:77], v[76:77], s[86:87] op_sel_hi:[1,0]
	v_rcp_f32_e32 v76, v76
	v_rcp_f32_e32 v77, v77
	v_exp_f32_e32 v83, v83
	v_add_f32_e32 v82, 1.0, v82
	v_rcp_f32_e32 v82, v82
	v_pk_mul_f32 v[74:75], v[74:75], v[76:77]
	v_pk_mul_f32 v[76:77], v[68:69], v[84:85] op_sel_hi:[1,0]
	v_exp_f32_e32 v76, v76
	v_exp_f32_e32 v77, v77
	v_add_f32_e32 v83, 1.0, v83
	v_rcp_f32_e32 v83, v83
	v_pk_add_f32 v[76:77], v[76:77], s[86:87] op_sel_hi:[1,0]
	v_rcp_f32_e32 v76, v76
	v_rcp_f32_e32 v77, v77
	v_pk_mul_f32 v[72:73], v[72:73], v[82:83]
	v_pk_mul_f32 v[74:75], v[80:81], v[74:75] op_sel_hi:[0,1]
	v_pk_mul_f32 v[72:73], v[80:81], v[72:73] op_sel_hi:[0,1]
	v_pk_mul_f32 v[64:65], v[64:65], v[76:77]
	s_nop 0
	v_pk_mul_f32 v[68:69], v[80:81], v[64:65] op_sel_hi:[0,1]
	v_pk_mul_f32 v[64:65], v[70:71], v[84:85] op_sel_hi:[1,0]
	v_exp_f32_e32 v64, v64
	v_exp_f32_e32 v65, v65
	s_nop 0
	v_pk_add_f32 v[64:65], v[64:65], s[86:87] op_sel_hi:[1,0]
	v_rcp_f32_e32 v64, v64
	v_rcp_f32_e32 v65, v65
	s_nop 0
	v_pk_mul_f32 v[64:65], v[66:67], v[64:65]
	s_nop 0
	v_pk_mul_f32 v[70:71], v[80:81], v[64:65] op_sel_hi:[0,1]
	v_cvt_pk_bf16_f32 v66, v68, v69
	v_mad_i64_i32 v[68:69], s[16:17], v81, s72, v[112:113]
	v_cvt_pk_bf16_f32 v64, v72, v73
	v_cvt_pk_bf16_f32 v65, v74, v75
	v_cvt_pk_bf16_f32 v67, v70, v71
	v_lshl_add_u64 v[68:69], v[68:69], 0, v[114:115]
	global_store_dwordx4 v[68:69], v[64:67], off
	s_nop 1
	v_add_u32_e32 v65, 0x80, v174
	v_and_b32_e32 v64, 0xff, v65
	v_lshl_add_u32 v64, v64, 2, s5
	ds_read_b32 v64, v64
	s_waitcnt lgkmcnt(0)
	v_mul_f32_e32 v68, 0xbfb8aa3b, v64
	v_pk_mul_f32 v[66:67], v[60:61], v[68:69] op_sel_hi:[1,0]
	v_pk_mul_f32 v[60:61], v[62:63], v[68:69] op_sel_hi:[1,0]
	v_exp_f32_e32 v60, v60
	v_exp_f32_e32 v61, v61
	v_mul_f32_e32 v64, v64, v64
	v_exp_f32_e32 v66, v66
	v_pk_add_f32 v[60:61], v[60:61], s[86:87] op_sel_hi:[1,0]
	v_rcp_f32_e32 v60, v60
	v_rcp_f32_e32 v61, v61
	v_exp_f32_e32 v67, v67
	v_add_f32_e32 v66, 1.0, v66
	v_rcp_f32_e32 v66, v66
	v_pk_mul_f32 v[58:59], v[58:59], v[60:61]
	v_pk_mul_f32 v[60:61], v[52:53], v[68:69] op_sel_hi:[1,0]
	v_exp_f32_e32 v60, v60
	v_exp_f32_e32 v61, v61
	v_add_f32_e32 v67, 1.0, v67
	v_rcp_f32_e32 v67, v67
	v_pk_add_f32 v[60:61], v[60:61], s[86:87] op_sel_hi:[1,0]
	v_rcp_f32_e32 v60, v60
	v_rcp_f32_e32 v61, v61
	v_pk_mul_f32 v[56:57], v[56:57], v[66:67]
	v_pk_mul_f32 v[58:59], v[64:65], v[58:59] op_sel_hi:[0,1]
	v_pk_mul_f32 v[56:57], v[64:65], v[56:57] op_sel_hi:[0,1]
	v_pk_mul_f32 v[48:49], v[48:49], v[60:61]
	s_nop 0
	v_pk_mul_f32 v[52:53], v[64:65], v[48:49] op_sel_hi:[0,1]
	v_pk_mul_f32 v[48:49], v[54:55], v[68:69] op_sel_hi:[1,0]
	v_exp_f32_e32 v48, v48
	v_exp_f32_e32 v49, v49
	s_nop 0
	v_pk_add_f32 v[48:49], v[48:49], s[86:87] op_sel_hi:[1,0]
	v_rcp_f32_e32 v48, v48
	v_rcp_f32_e32 v49, v49
	s_nop 0
	v_pk_mul_f32 v[48:49], v[50:51], v[48:49]
	s_nop 0
	v_pk_mul_f32 v[54:55], v[64:65], v[48:49] op_sel_hi:[0,1]
	v_cvt_pk_bf16_f32 v50, v52, v53
	v_mad_i64_i32 v[52:53], s[16:17], v65, s72, v[112:113]
	v_cvt_pk_bf16_f32 v48, v56, v57
	v_cvt_pk_bf16_f32 v49, v58, v59
	v_cvt_pk_bf16_f32 v51, v54, v55
	v_lshl_add_u64 v[52:53], v[52:53], 0, v[114:115]
	global_store_dwordx4 v[52:53], v[48:51], off
	s_nop 1
	v_add_u32_e32 v49, 0x90, v174
	v_and_b32_e32 v48, 0xff, v49
	v_lshl_add_u32 v48, v48, 2, s5
	ds_read_b32 v48, v48
	s_waitcnt lgkmcnt(0)
	v_mul_f32_e32 v52, 0xbfb8aa3b, v48
	v_pk_mul_f32 v[50:51], v[44:45], v[52:53] op_sel_hi:[1,0]
	v_pk_mul_f32 v[44:45], v[46:47], v[52:53] op_sel_hi:[1,0]
	v_exp_f32_e32 v44, v44
	v_exp_f32_e32 v45, v45
	v_mul_f32_e32 v48, v48, v48
	v_exp_f32_e32 v50, v50
	v_pk_add_f32 v[44:45], v[44:45], s[86:87] op_sel_hi:[1,0]
	v_rcp_f32_e32 v44, v44
	v_rcp_f32_e32 v45, v45
	v_exp_f32_e32 v51, v51
	v_add_f32_e32 v50, 1.0, v50
	v_rcp_f32_e32 v50, v50
	v_pk_mul_f32 v[42:43], v[42:43], v[44:45]
	v_pk_mul_f32 v[44:45], v[36:37], v[52:53] op_sel_hi:[1,0]
	v_exp_f32_e32 v44, v44
	v_exp_f32_e32 v45, v45
	v_add_f32_e32 v51, 1.0, v51
	v_rcp_f32_e32 v51, v51
	v_pk_add_f32 v[44:45], v[44:45], s[86:87] op_sel_hi:[1,0]
	v_rcp_f32_e32 v44, v44
	v_rcp_f32_e32 v45, v45
	v_pk_mul_f32 v[40:41], v[40:41], v[50:51]
	v_pk_mul_f32 v[42:43], v[48:49], v[42:43] op_sel_hi:[0,1]
	v_pk_mul_f32 v[40:41], v[48:49], v[40:41] op_sel_hi:[0,1]
	v_pk_mul_f32 v[32:33], v[32:33], v[44:45]
	s_nop 0
	v_pk_mul_f32 v[36:37], v[48:49], v[32:33] op_sel_hi:[0,1]
	v_pk_mul_f32 v[32:33], v[38:39], v[52:53] op_sel_hi:[1,0]
	v_exp_f32_e32 v32, v32
	v_exp_f32_e32 v33, v33
	s_nop 0
	v_pk_add_f32 v[32:33], v[32:33], s[86:87] op_sel_hi:[1,0]
	v_rcp_f32_e32 v32, v32
	v_rcp_f32_e32 v33, v33
	s_nop 0
	v_pk_mul_f32 v[32:33], v[34:35], v[32:33]
	s_nop 0
	v_pk_mul_f32 v[38:39], v[48:49], v[32:33] op_sel_hi:[0,1]
	v_cvt_pk_bf16_f32 v34, v36, v37
	v_mad_i64_i32 v[36:37], s[16:17], v49, s72, v[112:113]
	v_cvt_pk_bf16_f32 v32, v40, v41
	v_cvt_pk_bf16_f32 v33, v42, v43
	v_cvt_pk_bf16_f32 v35, v38, v39
	v_lshl_add_u64 v[36:37], v[36:37], 0, v[114:115]
	global_store_dwordx4 v[36:37], v[32:35], off
	s_nop 1
	v_add_u32_e32 v33, 0xa0, v174
	v_and_b32_e32 v32, 0xff, v33
	v_lshl_add_u32 v32, v32, 2, s5
	ds_read_b32 v32, v32
	s_waitcnt lgkmcnt(0)
	v_mul_f32_e32 v36, 0xbfb8aa3b, v32
	v_pk_mul_f32 v[34:35], v[28:29], v[36:37] op_sel_hi:[1,0]
	v_pk_mul_f32 v[28:29], v[30:31], v[36:37] op_sel_hi:[1,0]
	v_exp_f32_e32 v28, v28
	v_exp_f32_e32 v29, v29
	v_mul_f32_e32 v32, v32, v32
	v_exp_f32_e32 v34, v34
	v_pk_add_f32 v[28:29], v[28:29], s[86:87] op_sel_hi:[1,0]
	v_rcp_f32_e32 v28, v28
	v_rcp_f32_e32 v29, v29
	v_exp_f32_e32 v35, v35
	v_add_f32_e32 v34, 1.0, v34
	v_rcp_f32_e32 v34, v34
	v_pk_mul_f32 v[26:27], v[26:27], v[28:29]
	v_pk_mul_f32 v[28:29], v[20:21], v[36:37] op_sel_hi:[1,0]
	v_exp_f32_e32 v28, v28
	v_exp_f32_e32 v29, v29
	v_add_f32_e32 v35, 1.0, v35
	v_rcp_f32_e32 v35, v35
	v_pk_add_f32 v[28:29], v[28:29], s[86:87] op_sel_hi:[1,0]
	v_rcp_f32_e32 v28, v28
	v_rcp_f32_e32 v29, v29
	v_pk_mul_f32 v[24:25], v[24:25], v[34:35]
	v_pk_mul_f32 v[26:27], v[32:33], v[26:27] op_sel_hi:[0,1]
	v_pk_mul_f32 v[24:25], v[32:33], v[24:25] op_sel_hi:[0,1]
	v_pk_mul_f32 v[16:17], v[16:17], v[28:29]
	s_nop 0
	v_pk_mul_f32 v[20:21], v[32:33], v[16:17] op_sel_hi:[0,1]
	v_pk_mul_f32 v[16:17], v[22:23], v[36:37] op_sel_hi:[1,0]
	v_exp_f32_e32 v16, v16
	v_exp_f32_e32 v17, v17
	s_nop 0
	v_pk_add_f32 v[16:17], v[16:17], s[86:87] op_sel_hi:[1,0]
	v_rcp_f32_e32 v16, v16
	v_rcp_f32_e32 v17, v17
	s_nop 0
	v_pk_mul_f32 v[16:17], v[18:19], v[16:17]
	s_nop 0
	v_pk_mul_f32 v[22:23], v[32:33], v[16:17] op_sel_hi:[0,1]
	v_cvt_pk_bf16_f32 v18, v20, v21
	v_mad_i64_i32 v[20:21], s[16:17], v33, s72, v[112:113]
	v_cvt_pk_bf16_f32 v16, v24, v25
	v_cvt_pk_bf16_f32 v17, v26, v27
	v_cvt_pk_bf16_f32 v19, v22, v23
	v_lshl_add_u64 v[20:21], v[20:21], 0, v[114:115]
	global_store_dwordx4 v[20:21], v[16:19], off
	s_nop 1
	v_add_u32_e32 v16, 0xb0, v174
	v_and_b32_e32 v17, 0xff, v16
	v_lshl_add_u32 v17, v17, 2, s5
	ds_read_b32 v17, v17
	s_waitcnt lgkmcnt(0)
	v_mul_f32_e32 v19, 0xbfb8aa3b, v17
	v_mul_f32_e32 v18, v17, v17
	v_mul_f32_e32 v17, v8, v19
	v_exp_f32_e32 v17, v17
	v_pk_mul_f32 v[10:11], v[10:11], v[18:19] op_sel:[0,1] op_sel_hi:[1,1]
	v_exp_f32_e32 v10, v10
	v_add_f32_e32 v17, 1.0, v17
	v_rcp_f32_e32 v20, v17
	v_mul_f32_e32 v17, v9, v19
	v_pk_mul_f32 v[8:9], v[8:9], v[12:13]
	v_pk_mul_f32 v[12:13], v[4:5], v[18:19] op_sel:[0,1] op_sel_hi:[1,1]
	v_exp_f32_e32 v12, v12
	v_exp_f32_e32 v13, v13
	v_exp_f32_e32 v17, v17
	v_exp_f32_e32 v11, v11
	v_pk_add_f32 v[12:13], v[12:13], s[86:87] op_sel_hi:[1,0]
	v_rcp_f32_e32 v12, v12
	v_rcp_f32_e32 v13, v13
	v_add_f32_e32 v17, 1.0, v17
	v_pk_add_f32 v[10:11], v[10:11], s[86:87] op_sel_hi:[1,0]
	v_pk_mul_f32 v[0:1], v[0:1], v[12:13]
	v_rcp_f32_e32 v21, v17
	v_pk_mul_f32 v[4:5], v[18:19], v[0:1] op_sel_hi:[0,1]
	v_pk_mul_f32 v[0:1], v[6:7], v[18:19] op_sel:[0,1] op_sel_hi:[1,1]
	v_exp_f32_e32 v0, v0
	v_exp_f32_e32 v1, v1
	v_rcp_f32_e32 v10, v10
	v_rcp_f32_e32 v11, v11
	v_pk_add_f32 v[0:1], v[0:1], s[86:87] op_sel_hi:[1,0]
	v_rcp_f32_e32 v0, v0
	v_rcp_f32_e32 v1, v1
	v_pk_mul_f32 v[8:9], v[8:9], v[20:21]
	v_pk_mul_f32 v[10:11], v[14:15], v[10:11]
	v_pk_mul_f32 v[8:9], v[18:19], v[8:9] op_sel_hi:[0,1]
	v_pk_mul_f32 v[0:1], v[2:3], v[0:1]
	v_pk_mul_f32 v[10:11], v[18:19], v[10:11] op_sel_hi:[0,1]
	v_pk_mul_f32 v[6:7], v[18:19], v[0:1] op_sel_hi:[0,1]
	v_cvt_pk_bf16_f32 v2, v4, v5
	v_mad_i64_i32 v[4:5], s[16:17], v16, s72, v[112:113]
	v_cvt_pk_bf16_f32 v0, v8, v9
	v_cvt_pk_bf16_f32 v1, v10, v11
	v_cvt_pk_bf16_f32 v3, v6, v7
	v_lshl_add_u64 v[4:5], v[4:5], 0, v[114:115]
	global_store_dwordx4 v[4:5], v[0:3], off
	s_andn2_b64 vcc, exec, s[38:39]
	s_mov_b64 s[16:17], -1
	s_cbranch_vccnz .LBB0_625
